# attention: lazy accumulator rescale (running max only advanced when it grows by more than 8 in log2 units; exact, softmax shift invariance)
# baseline (speedup 1.0000x reference)
; DEV void attn_unit(const Params& P, int b, int qb, int h) {
;     ...
;       float mx = s0[0];
; #pragma unroll
;       for (int r = 1; r < 16; ++r) mx = fmaxf(mx, s0[r]);
; #pragma unroll
;       for (int r = 0; r < 16; ++r) mx = fmaxf(mx, s1[r]);
;       mx = fmaxf(mx, __shfl_xor(mx, 32));
;       const float mn = fmaxf(m, mx);
;       const float alpha = __builtin_amdgcn_exp2f(m - mn);
;       m = mn;
;       float ls = 0.f;
; #pragma unroll
;       for (int r = 0; r < 16; ++r) { s0[r] = __builtin_amdgcn_exp2f(s0[r] - mn); s1[r] = __builtin_amdgcn_exp2f(s1[r] - mn); ls += s0[r] + s1[r]; }
;       l = l * alpha + ls;
;       if (__any(alpha != 1.f)) {
; #pragma unroll
;         for (int r = 0; r < 16; ++r) { o[0][r] *= alpha; o[1][r] *= alpha; }
;       }
.LBB0_187:
	s_or_b64 exec, exec, s[26:27]
	s_nop 6
	v_max_f32_e32 v126, v49, v49
	v_max_f32_e32 v148, v48, v48
	v_max_f32_e32 v126, v148, v126
	v_max3_f32 v126, v126, v50, v51
	v_max3_f32 v126, v126, v52, v53
	v_max3_f32 v126, v126, v54, v55
	v_max3_f32 v126, v126, v56, v57
	v_max3_f32 v126, v126, v58, v59
	v_max3_f32 v126, v126, v60, v61
	v_max3_f32 v126, v126, v62, v63
	v_max3_f32 v126, v126, v32, v33
	v_max3_f32 v126, v126, v34, v35
	v_max3_f32 v126, v126, v36, v37
	v_max3_f32 v126, v126, v38, v39
	v_max3_f32 v126, v126, v40, v41
	v_max3_f32 v126, v126, v42, v43
	v_max3_f32 v126, v126, v44, v45
	v_max3_f32 v126, v126, v46, v47
	ds_bpermute_b32 v148, v155, v126
	s_waitcnt lgkmcnt(0)
	v_max3_f32 v148, v125, v126, v148
	v_sub_f32_e32 v233, v125, v148
	v_cmp_gt_f32_e32 vcc, 0xc1000000, v233
	v_cndmask_b32_e32 v148, v125, v148, vcc
	v_sub_f32_e32 v125, v125, v148
	v_exp_f32_e32 v126, v125
	s_nop 0
	v_cmp_neq_f32_e32 vcc, 1.0, v126
	s_cbranch_vccz .LBB0_182
	v_pk_mul_f32 v[14:15], v[14:15], v[126:127] op_sel_hi:[1,0]
	v_pk_mul_f32 v[12:13], v[12:13], v[126:127] op_sel_hi:[1,0]
	v_pk_mul_f32 v[10:11], v[10:11], v[126:127] op_sel_hi:[1,0]
	v_pk_mul_f32 v[8:9], v[8:9], v[126:127] op_sel_hi:[1,0]
	v_pk_mul_f32 v[6:7], v[6:7], v[126:127] op_sel_hi:[1,0]
	v_pk_mul_f32 v[4:5], v[4:5], v[126:127] op_sel_hi:[1,0]
	v_pk_mul_f32 v[2:3], v[2:3], v[126:127] op_sel_hi:[1,0]
	v_pk_mul_f32 v[0:1], v[0:1], v[126:127] op_sel_hi:[1,0]
	v_pk_mul_f32 v[30:31], v[30:31], v[126:127] op_sel_hi:[1,0]
	v_pk_mul_f32 v[28:29], v[28:29], v[126:127] op_sel_hi:[1,0]
	v_pk_mul_f32 v[26:27], v[26:27], v[126:127] op_sel_hi:[1,0]
	v_pk_mul_f32 v[24:25], v[24:25], v[126:127] op_sel_hi:[1,0]
	v_pk_mul_f32 v[22:23], v[22:23], v[126:127] op_sel_hi:[1,0]
	v_pk_mul_f32 v[20:21], v[20:21], v[126:127] op_sel_hi:[1,0]
	v_pk_mul_f32 v[18:19], v[18:19], v[126:127] op_sel_hi:[1,0]
	v_pk_mul_f32 v[16:17], v[16:17], v[126:127] op_sel_hi:[1,0]
	s_branch .LBB0_182
